# rowwise phase 2 (first adaLN) hand-rewritten as well: scalar row decode, next-row prefetch, table loads issued together
# speedup vs baseline: 1.0379x; 1.0007x over previous
; DI int get_tid() { int t = threadIdx.x; asm volatile("" : "+v"(t)); return t; }
; DI int get_bid() { int t = blockIdx.x; asm volatile("" : "+s"(t)); return t; }
; DI void phase_rowwise(PP p, bool first, const u16* src, const float* g_post, int l_res, int gate_idx,
;                       bool write_h, const float* g_pre, int l_mod, int shift_idx, int scale_idx, bool skip_ctx) {
;   const int lane = get_tid() & 63, w = get_tid() >> 6;
;   u16* H = (u16*)(p->ws + H_OFF);
;   for (int r = get_bid() * 4 + w; r < ROWS; r += gridDim.x * 4) {
;     int b = r / TT, t = r - b * TT;
;     if (skip_ctx && t < CTX) continue;
;     int s = t < CTX ? 4 : b;
;     const float* xin = xrow_in(p, r, first);
;     float x[16];
; #pragma unroll
;     for (int i = 0; i < 4; ++i) { F4 v = *(const F4*)(xin + i * 256 + lane * 4); x[4 * i] = v.x; x[4 * i + 1] = v.y; x[4 * i + 2] = v.z; x[4 * i + 3] = v.w; }
; DI void run_phase(PP p, int ph, unsigned char* lds) {
;     ...
;     case 2: phase_rowwise(p, true, nullptr, nullptr, 0, 0, true, p->in[I_NMPRE], 0, 0, 1, false); break;
.LBB0_1190:
	s_andn2_b64 vcc, exec, s[0:1]
	s_cbranch_vccnz .LBB0_1195
	v_lshrrev_b32_e32 v0, 6, v163
	v_readlane_b32 s2, v249, 0
	v_readfirstlane_b32 s3, v0
	v_and_b32_e32 v0, 63, v163
	s_lshl_b32 s0, s2, 2
	s_add_i32 s0, s0, s3
	v_lshlrev_b32_e32 v2, 4, v0
	v_lshlrev_b32_e32 v3, 3, v0
	v_xor_b32_e32 v4, 32, v0
	v_xor_b32_e32 v5, 16, v0
	v_xor_b32_e32 v6, 8, v0
	v_xor_b32_e32 v7, 4, v0
	v_xor_b32_e32 v8, 2, v0
	v_xor_b32_e32 v9, 1, v0
	v_lshlrev_b32_e32 v4, 2, v4
	v_lshlrev_b32_e32 v5, 2, v5
	v_lshlrev_b32_e32 v6, 2, v6
	v_lshlrev_b32_e32 v7, 2, v7
	v_lshlrev_b32_e32 v8, 2, v8
	v_lshlrev_b32_e32 v9, 2, v9
	v_mov_b32_e32 v43, 0
	v_mov_b32_e32 v229, 0
	v_readlane_b32 s12, v251, 35
	v_readlane_b32 s13, v251, 36
	s_nop 0
	s_load_dwordx2 s[4:5], s[12:13], 0x30
	s_load_dwordx2 s[6:7], s[12:13], 0x0
	s_load_dwordx2 s[8:9], s[12:13], 0x10
	s_waitcnt lgkmcnt(0)
	v_mov_b32_e32 v42, v2
	v_lshl_add_u64 v[172:173], s[4:5], 0, v[42:43]
	v_mov_b32_e32 v234, s6
	v_mov_b32_e32 v235, s7
	v_mov_b32_e32 v236, s8
	v_mov_b32_e32 v237, s9
	s_add_u32 s6, s48, 0x2b00000
	s_addc_u32 s7, s49, 0
	v_lshl_add_u64 v[176:177], s[6:7], 0, v[42:43]
	s_add_u32 s6, s6, 0x1000
	s_addc_u32 s7, s7, 0
	v_lshl_add_u64 v[178:179], s[6:7], 0, v[42:43]
	v_mov_b32_e32 v42, v3
	s_add_u32 s6, s48, 0x3900000
	s_addc_u32 s7, s49, 0
	v_lshl_add_u64 v[182:183], s[6:7], 0, v[42:43]
	s_cmp_ge_u32 s0, 0x8400
	s_cbranch_scc1 .Lrw2_done
	s_cmp_ge_u32 s0, 0x2100
	s_cselect_b32 s2, 1, 0
	s_cmp_ge_u32 s0, 0x4200
	s_addc_u32 s2, s2, 0
	s_cmp_ge_u32 s0, 0x6300
	s_addc_u32 s2, s2, 0
	s_mul_i32 s3, s2, 0x2100
	s_sub_i32 s3, s0, s3
	s_lshl_b32 s7, s2, 8
	s_add_i32 s7, s7, s3
	s_lshl_b32 s9, s2, 13
	s_add_i32 s9, s9, s3
	s_add_i32 s9, s9, 0xffffff00
	s_cmp_lt_u32 s3, 0x100
	s_cselect_b32 s7, s7, s9
	s_cselect_b32 s5, 4, s2
	s_cselect_b64 s[12:13], -1, 0
	s_lshl_b32 s7, s7, 12
	v_add_u32_e32 v42, s7, v2
	v_cndmask_b32_e64 v190, v234, v236, s[12:13]
	v_cndmask_b32_e64 v191, v235, v237, s[12:13]
	v_lshl_add_u64 v[190:191], v[190:191], 0, v[42:43]
	global_load_dwordx4 v[26:29], v[190:191], off
	global_load_dwordx4 v[30:33], v[190:191], off offset:1024
	global_load_dwordx4 v[34:37], v[190:191], off offset:2048
	global_load_dwordx4 v[38:41], v[190:191], off offset:3072
	s_waitcnt vmcnt(0)
; DI int get_bid() { int t = blockIdx.x; asm volatile("" : "+s"(t)); return t; }
; DI unsigned pack2(float a, float b) { F2 v = {a, b}; B2 r = __builtin_convertvector(v, B2); return __builtin_bit_cast(unsigned, r); }
; DI float wave_sum(float v) { for (int o = 32; o > 0; o >>= 1) v += __shfl_xor(v, o); return v; }
; DI const float* modvec(PP p, int l, int s, int idx) { return (const float*)(p->ws + S_MOD) + ((size_t)(l * 5 + s) * 6 + idx) * DM; }
; DI void phase_rowwise(PP p, bool first, const u16* src, const float* g_post, int l_res, int gate_idx,
;                       bool write_h, const float* g_pre, int l_mod, int shift_idx, int scale_idx, bool skip_ctx) {
;     ...
;   for (int r = get_bid() * 4 + w; r < ROWS; r += gridDim.x * 4) {
;     int b = r / TT, t = r - b * TT;
;     if (skip_ctx && t < CTX) continue;
;     int s = t < CTX ? 4 : b;
;     const float* xin = xrow_in(p, r, first);
;     float x[16];
; #pragma unroll
;     for (int i = 0; i < 4; ++i) { F4 v = *(const F4*)(xin + i * 256 + lane * 4); x[4 * i] = v.x; x[4 * i + 1] = v.y; x[4 * i + 2] = v.z; x[4 * i + 3] = v.w; }
;     ...
;     if (write_h) {
;       float ss = 0.f;
; #pragma unroll
;       for (int i = 0; i < 16; ++i) ss += x[i] * x[i];
;       ss = wave_sum(ss);
;       float rstd = rsqrtf(ss * (1.f / DM) + EPS);
;       const float* sh = modvec(p, l_mod, s, shift_idx); const float* sc = modvec(p, l_mod, s, scale_idx);
; #pragma unroll
;       for (int i = 0; i < 4; ++i) {
;         int k = i * 256 + lane * 4;
;         F4 g = *(const F4*)(g_pre + k); F4 a = *(const F4*)(sh + k); F4 c = *(const F4*)(sc + k);
;         float h0 = x[4 * i] * rstd * g.x * (1.f + c.x) + a.x, h1 = x[4 * i + 1] * rstd * g.y * (1.f + c.y) + a.y;
;         float h2 = x[4 * i + 2] * rstd * g.z * (1.f + c.z) + a.z, h3 = x[4 * i + 3] * rstd * g.w * (1.f + c.w) + a.w;
;         *(U2*)(H + (size_t)r * DM + k) = mku2(pack2(h0, h1), pack2(h2, h3));
;       }
;     }
.Lrw2_loop:
	v_mov_b32_e32 v10, v26
	v_mov_b32_e32 v11, v27
	v_mov_b32_e32 v12, v28
	v_mov_b32_e32 v13, v29
	v_mov_b32_e32 v14, v30
	v_mov_b32_e32 v15, v31
	v_mov_b32_e32 v16, v32
	v_mov_b32_e32 v17, v33
	v_mov_b32_e32 v18, v34
	v_mov_b32_e32 v19, v35
	v_mov_b32_e32 v20, v36
	v_mov_b32_e32 v21, v37
	v_mov_b32_e32 v22, v38
	v_mov_b32_e32 v23, v39
	v_mov_b32_e32 v24, v40
	v_mov_b32_e32 v25, v41
	s_mov_b32 s4, s5
	s_mul_i32 s7, s4, 0x6000
	v_mov_b32_e32 v42, s7
	v_lshl_add_u64 v[222:223], v[176:177], 0, v[42:43]
	v_lshl_add_u64 v[224:225], v[178:179], 0, v[42:43]
	s_lshl_b32 s7, s0, 11
	v_mov_b32_e32 v42, s7
	v_lshl_add_u64 v[218:219], v[182:183], 0, v[42:43]
	global_load_dwordx4 v[118:121], v[172:173], off
	global_load_dwordx4 v[122:125], v[172:173], off offset:1024
	global_load_dwordx4 v[126:129], v[172:173], off offset:2048
	global_load_dwordx4 v[130:133], v[172:173], off offset:3072
	global_load_dwordx4 v[134:137], v[222:223], off
	global_load_dwordx4 v[138:141], v[222:223], off offset:1024
	global_load_dwordx4 v[142:145], v[222:223], off offset:2048
	global_load_dwordx4 v[146:149], v[222:223], off offset:3072
	global_load_dwordx4 v[150:153], v[224:225], off
	global_load_dwordx4 v[154:157], v[224:225], off offset:1024
	global_load_dwordx4 v[158:161], v[224:225], off offset:2048
	global_load_dwordx4 v[166:169], v[224:225], off offset:3072
	s_add_i32 s1, s0, s90
	s_mov_b32 s8, 0
	s_cmp_ge_u32 s1, 0x8400
	s_cselect_b32 s8, 1, 0
	s_cselect_b32 s1, s0, s1
	s_cmp_ge_u32 s1, 0x2100
	s_cselect_b32 s2, 1, 0
	s_cmp_ge_u32 s1, 0x4200
	s_addc_u32 s2, s2, 0
	s_cmp_ge_u32 s1, 0x6300
	s_addc_u32 s2, s2, 0
	s_mul_i32 s3, s2, 0x2100
	s_sub_i32 s3, s1, s3
	s_lshl_b32 s7, s2, 8
	s_add_i32 s7, s7, s3
	s_lshl_b32 s9, s2, 13
	s_add_i32 s9, s9, s3
	s_add_i32 s9, s9, 0xffffff00
	s_cmp_lt_u32 s3, 0x100
	s_cselect_b32 s7, s7, s9
	s_cselect_b32 s5, 4, s2
	s_cselect_b64 s[12:13], -1, 0
	s_lshl_b32 s7, s7, 12
	v_add_u32_e32 v42, s7, v2
	v_cndmask_b32_e64 v190, v234, v236, s[12:13]
	v_cndmask_b32_e64 v191, v235, v237, s[12:13]
	v_lshl_add_u64 v[190:191], v[190:191], 0, v[42:43]
	global_load_dwordx4 v[26:29], v[190:191], off
	global_load_dwordx4 v[30:33], v[190:191], off offset:1024
	global_load_dwordx4 v[34:37], v[190:191], off offset:2048
	global_load_dwordx4 v[38:41], v[190:191], off offset:3072
	v_mul_f32_e32 v226, v11, v11
	v_fmac_f32_e32 v226, v10, v10
	v_fmac_f32_e32 v226, v12, v12
	v_fmac_f32_e32 v226, v13, v13
	v_fmac_f32_e32 v226, v14, v14
	v_fmac_f32_e32 v226, v15, v15
	v_fmac_f32_e32 v226, v16, v16
	v_fmac_f32_e32 v226, v17, v17
	v_fmac_f32_e32 v226, v18, v18
	v_fmac_f32_e32 v226, v19, v19
	v_fmac_f32_e32 v226, v20, v20
	v_fmac_f32_e32 v226, v21, v21
	v_mul_f32_e32 v227, v22, v22
	v_add_f32_e32 v226, v227, v226
	v_mul_f32_e32 v227, v23, v23
	v_add_f32_e32 v226, v227, v226
	v_mul_f32_e32 v227, v24, v24
	v_add_f32_e32 v226, v227, v226
	v_mul_f32_e32 v227, v25, v25
	v_add_f32_e32 v226, v227, v226
	ds_bpermute_b32 v227, v4, v226
	s_waitcnt lgkmcnt(0)
	v_add_f32_e32 v226, v226, v227
	ds_bpermute_b32 v227, v5, v226
	s_waitcnt lgkmcnt(0)
	v_add_f32_e32 v226, v226, v227
	ds_bpermute_b32 v227, v6, v226
	s_waitcnt lgkmcnt(0)
	v_add_f32_e32 v226, v226, v227
	ds_bpermute_b32 v227, v7, v226
	s_waitcnt lgkmcnt(0)
	v_add_f32_e32 v226, v226, v227
	ds_bpermute_b32 v227, v8, v226
	s_waitcnt lgkmcnt(0)
	v_add_f32_e32 v226, v226, v227
	ds_bpermute_b32 v227, v9, v226
	s_waitcnt lgkmcnt(0)
	v_add_f32_e32 v226, v226, v227
	v_fmamk_f32 v226, v226, 0x3a800000, v162
	s_mov_b32 s7, 0x800000
	v_cmp_gt_f32_e32 vcc, s7, v226
	v_mul_f32_e32 v227, 0x4b800000, v226
	s_nop 0
	v_cndmask_b32_e32 v226, v226, v227, vcc
	v_rsq_f32_e32 v226, v226
	s_nop 0
	v_mul_f32_e32 v227, 0x45800000, v226
	v_cndmask_b32_e32 v228, v226, v227, vcc
	s_waitcnt vmcnt(4)
	v_pk_mul_f32 v[10:11], v[10:11], v[228:229] op_sel_hi:[1,0]
	v_pk_mul_f32 v[10:11], v[118:119], v[10:11]
	v_pk_add_f32 v[44:45], v[150:151], 1.0 op_sel_hi:[1,0]
	s_nop 0
	v_pk_fma_f32 v[10:11], v[44:45], v[10:11], v[134:135]
	v_pk_mul_f32 v[12:13], v[12:13], v[228:229] op_sel_hi:[1,0]
	v_pk_mul_f32 v[12:13], v[120:121], v[12:13]
	v_pk_add_f32 v[46:47], v[152:153], 1.0 op_sel_hi:[1,0]
	s_nop 0
	v_pk_fma_f32 v[12:13], v[46:47], v[12:13], v[136:137]
	v_cvt_pk_bf16_f32 v48, v10, v11
	v_cvt_pk_bf16_f32 v49, v12, v13
	global_store_dwordx2 v[218:219], v[48:49], off
	s_nop 1
	v_pk_mul_f32 v[14:15], v[14:15], v[228:229] op_sel_hi:[1,0]
	v_pk_mul_f32 v[14:15], v[122:123], v[14:15]
	v_pk_add_f32 v[44:45], v[154:155], 1.0 op_sel_hi:[1,0]
	s_nop 0
	v_pk_fma_f32 v[14:15], v[44:45], v[14:15], v[138:139]
	v_pk_mul_f32 v[16:17], v[16:17], v[228:229] op_sel_hi:[1,0]
	v_pk_mul_f32 v[16:17], v[124:125], v[16:17]
	v_pk_add_f32 v[46:47], v[156:157], 1.0 op_sel_hi:[1,0]
	s_nop 0
	v_pk_fma_f32 v[16:17], v[46:47], v[16:17], v[140:141]
	v_cvt_pk_bf16_f32 v48, v14, v15
	v_cvt_pk_bf16_f32 v49, v16, v17
	global_store_dwordx2 v[218:219], v[48:49], off offset:512
	s_nop 1
	v_pk_mul_f32 v[18:19], v[18:19], v[228:229] op_sel_hi:[1,0]
	v_pk_mul_f32 v[18:19], v[126:127], v[18:19]
	v_pk_add_f32 v[44:45], v[158:159], 1.0 op_sel_hi:[1,0]
	s_nop 0
	v_pk_fma_f32 v[18:19], v[44:45], v[18:19], v[142:143]
	v_pk_mul_f32 v[20:21], v[20:21], v[228:229] op_sel_hi:[1,0]
	v_pk_mul_f32 v[20:21], v[128:129], v[20:21]
	v_pk_add_f32 v[46:47], v[160:161], 1.0 op_sel_hi:[1,0]
	s_nop 0
	v_pk_fma_f32 v[20:21], v[46:47], v[20:21], v[144:145]
	v_cvt_pk_bf16_f32 v48, v18, v19
	v_cvt_pk_bf16_f32 v49, v20, v21
	global_store_dwordx2 v[218:219], v[48:49], off offset:1024
	s_nop 1
	v_pk_mul_f32 v[22:23], v[22:23], v[228:229] op_sel_hi:[1,0]
	v_pk_mul_f32 v[22:23], v[130:131], v[22:23]
	v_pk_add_f32 v[44:45], v[166:167], 1.0 op_sel_hi:[1,0]
	s_nop 0
	v_pk_fma_f32 v[22:23], v[44:45], v[22:23], v[146:147]
	v_pk_mul_f32 v[24:25], v[24:25], v[228:229] op_sel_hi:[1,0]
	v_pk_mul_f32 v[24:25], v[132:133], v[24:25]
	v_pk_add_f32 v[46:47], v[168:169], 1.0 op_sel_hi:[1,0]
	s_nop 0
	v_pk_fma_f32 v[24:25], v[46:47], v[24:25], v[148:149]
	v_cvt_pk_bf16_f32 v48, v22, v23
	v_cvt_pk_bf16_f32 v49, v24, v25
	global_store_dwordx2 v[218:219], v[48:49], off offset:1536
	s_nop 1
	s_waitcnt vmcnt(4)
	s_cmp_eq_u32 s8, 1
	s_cbranch_scc1 .Lrw2_done
	s_mov_b32 s0, s1
	s_branch .Lrw2_loop
.Lrw2_done:
	s_waitcnt vmcnt(0)
.LBB0_1194:
	s_or_b64 exec, exec, s[0:1]
